# retention chain S/O stages: wave-uniform EXEC save/restore pairs around conditional MFMAs removed (all MFMAs issued; skipped ones only add zeros / masked tiles)
# baseline (speedup 1.0000x reference)
; #define MFMA16(a, b, c) __builtin_amdgcn_mfma_f32_16x16x32_bf16((a), (b), (c), 0, 0, 0)
; template <bool STORE> __device__ __forceinline__ void ret_chain(LAS unsigned char* lds, int b, int h, bf16* Qb, const bf16* Kb, const bf16* Vb, const bf16* Gb, const f32x2* tab, float* s_out) {
;     ...
; #pragma unroll
;         for (int ks = 0; ks < 4; ++ks) {
;             const int kel = ks * 32 + quad * 8;
;             bf16x8 qf[4], kf[2], sf[2];
; #pragma unroll
;             for (int ti = 0; ti < 4; ++ti) qf[ti] = ldfrag(lds + RG0, 64 * wr + 16 * ti + l15, kel);
; #pragma unroll
;             for (int t = 0; t < 2; ++t) { kf[t] = ldfrag(lds + RG1, 32 * wc + 16 * t + l15, kel); sf[t] = ldfrag(lds + RG3, 32 * wc + 16 * t + l15, kel); }
; #pragma unroll
;             for (int ti = 0; ti < 4; ++ti)
; #pragma unroll
;                 for (int t = 0; t < 2; ++t) { if (32 * wc + 16 * t <= 64 * wr + 16 * ti + 15) acc_p[ti][t] = MFMA16(kf[t], qf[ti], acc_p[ti][t]);
;                     acc_o[ti][t] = MFMA16(sf[t], qf[ti], acc_o[ti][t]); }
;         }
.LBB0_321:
	v_add_u32_e32 v190, v197, v199
	v_add_u32_e32 v191, v197, v223
	ds_read_b128 v[84:87], v190
	ds_read_b128 v[92:95], v190 offset:4352
	ds_read_b128 v[100:103], v190 offset:8704
	ds_read_b128 v[108:111], v190 offset:13056
	ds_read_b128 v[144:147], v191 offset:34816
	ds_read_b128 v[152:155], v191 offset:39168
	ds_read_b128 v[112:115], v242
	ds_read_b128 v[148:151], v242 offset:4352
	v_mov_b64_e32 v[142:143], v[2:3]
	v_mov_b64_e32 v[140:141], v[0:1]
	s_waitcnt lgkmcnt(3)
	v_mfma_f32_16x16x32_bf16 v[140:143], v[144:147], v[84:87], v[0:3]
.LBB0_323:
	s_waitcnt lgkmcnt(1)
	v_mfma_f32_16x16x32_bf16 v[88:91], v[112:115], v[84:87], v[0:3]
	v_mov_b64_e32 v[130:131], v[2:3]
	v_mov_b64_e32 v[128:129], v[0:1]
	v_mfma_f32_16x16x32_bf16 v[128:131], v[152:155], v[84:87], v[0:3]
	s_waitcnt lgkmcnt(0)
	v_mfma_f32_16x16x32_bf16 v[84:87], v[148:151], v[84:87], v[0:3]
	v_mov_b64_e32 v[122:123], v[2:3]
	v_mov_b64_e32 v[120:121], v[0:1]
	v_mfma_f32_16x16x32_bf16 v[120:123], v[144:147], v[92:95], v[0:3]
	v_mfma_f32_16x16x32_bf16 v[96:99], v[112:115], v[92:95], v[0:3]
	v_mov_b64_e32 v[118:119], v[2:3]
	v_mov_b64_e32 v[116:117], v[0:1]
	v_mfma_f32_16x16x32_bf16 v[116:119], v[152:155], v[92:95], v[0:3]
	v_mfma_f32_16x16x32_bf16 v[92:95], v[148:151], v[92:95], v[0:3]
	v_mov_b64_e32 v[126:127], v[2:3]
	v_mov_b64_e32 v[124:125], v[0:1]
	v_mfma_f32_16x16x32_bf16 v[124:127], v[144:147], v[100:103], v[0:3]
	v_mfma_f32_16x16x32_bf16 v[104:107], v[112:115], v[100:103], v[0:3]
	v_mov_b64_e32 v[134:135], v[2:3]
	v_mov_b64_e32 v[132:133], v[0:1]
	v_mfma_f32_16x16x32_bf16 v[132:135], v[152:155], v[100:103], v[0:3]
	v_mfma_f32_16x16x32_bf16 v[100:103], v[148:151], v[100:103], v[0:3]
	v_mov_b64_e32 v[138:139], v[2:3]
	v_mov_b64_e32 v[136:137], v[0:1]
	v_mfma_f32_16x16x32_bf16 v[136:139], v[144:147], v[108:111], v[0:3]
	v_mfma_f32_16x16x32_bf16 v[112:115], v[112:115], v[108:111], v[0:3]
	v_mov_b64_e32 v[146:147], v[2:3]
	v_mov_b64_e32 v[144:145], v[0:1]
	v_mfma_f32_16x16x32_bf16 v[144:147], v[152:155], v[108:111], v[0:3]
	v_mfma_f32_16x16x32_bf16 v[108:111], v[148:151], v[108:111], v[0:3]
	ds_read_b128 v[176:179], v190 offset:64
	ds_read_b128 v[172:175], v190 offset:4416
	ds_read_b128 v[168:171], v190 offset:8768
	ds_read_b128 v[148:151], v190 offset:13120
	ds_read_b128 v[160:163], v191 offset:34880
	v_add_u32_e32 v152, v225, v224
	ds_read_b128 v[164:167], v152
	ds_read_b128 v[152:155], v191 offset:39232
	ds_read_b128 v[156:159], v243 offset:4352
	s_waitcnt lgkmcnt(3)
	v_mfma_f32_16x16x32_bf16 v[140:143], v[160:163], v[176:179], v[140:143]
.LBB0_339:
	s_waitcnt lgkmcnt(2)
	v_mfma_f32_16x16x32_bf16 v[88:91], v[164:167], v[176:179], v[88:91]
	s_waitcnt lgkmcnt(1)
	v_mfma_f32_16x16x32_bf16 v[128:131], v[152:155], v[176:179], v[128:131]
.LBB0_341:
	s_waitcnt lgkmcnt(0)
	v_mfma_f32_16x16x32_bf16 v[84:87], v[156:159], v[176:179], v[84:87]
	v_mfma_f32_16x16x32_bf16 v[120:123], v[160:163], v[172:175], v[120:123]
	v_mfma_f32_16x16x32_bf16 v[96:99], v[164:167], v[172:175], v[96:99]
	v_mfma_f32_16x16x32_bf16 v[116:119], v[152:155], v[172:175], v[116:119]
	v_mfma_f32_16x16x32_bf16 v[92:95], v[156:159], v[172:175], v[92:95]
	v_mfma_f32_16x16x32_bf16 v[124:127], v[160:163], v[168:171], v[124:127]
	v_mfma_f32_16x16x32_bf16 v[104:107], v[164:167], v[168:171], v[104:107]
	v_mfma_f32_16x16x32_bf16 v[132:135], v[152:155], v[168:171], v[132:135]
	v_mfma_f32_16x16x32_bf16 v[100:103], v[156:159], v[168:171], v[100:103]
	v_mfma_f32_16x16x32_bf16 v[136:139], v[160:163], v[148:151], v[136:139]
	v_mfma_f32_16x16x32_bf16 v[112:115], v[164:167], v[148:151], v[112:115]
	v_mfma_f32_16x16x32_bf16 v[144:147], v[152:155], v[148:151], v[144:147]
	v_mfma_f32_16x16x32_bf16 v[108:111], v[156:159], v[148:151], v[108:111]
	ds_read_b128 v[148:151], v190 offset:128
	ds_read_b128 v[152:155], v190 offset:4480
	ds_read_b128 v[156:159], v190 offset:8832
	ds_read_b128 v[164:167], v190 offset:13184
	ds_read_b128 v[160:163], v191 offset:34944
	v_add_u32_e32 v168, v225, v226
	ds_read_b128 v[176:179], v168
	ds_read_b128 v[168:171], v191 offset:39296
	ds_read_b128 v[172:175], v244 offset:4352
	s_waitcnt lgkmcnt(3)
	v_mfma_f32_16x16x32_bf16 v[140:143], v[160:163], v[148:151], v[140:143]
.LBB0_355:
	s_waitcnt lgkmcnt(2)
	v_mfma_f32_16x16x32_bf16 v[88:91], v[176:179], v[148:151], v[88:91]
	s_waitcnt lgkmcnt(1)
	v_mfma_f32_16x16x32_bf16 v[128:131], v[168:171], v[148:151], v[128:131]
.LBB0_357:
	s_waitcnt lgkmcnt(0)
	v_mfma_f32_16x16x32_bf16 v[148:151], v[172:175], v[148:151], v[84:87]
	v_mfma_f32_16x16x32_bf16 v[120:123], v[160:163], v[152:155], v[120:123]
	v_mfma_f32_16x16x32_bf16 v[96:99], v[176:179], v[152:155], v[96:99]
	v_mfma_f32_16x16x32_bf16 v[116:119], v[168:171], v[152:155], v[116:119]
	v_mfma_f32_16x16x32_bf16 v[92:95], v[172:175], v[152:155], v[92:95]
	v_mfma_f32_16x16x32_bf16 v[124:127], v[160:163], v[156:159], v[124:127]
	v_mfma_f32_16x16x32_bf16 v[152:155], v[176:179], v[156:159], v[104:107]
	v_mfma_f32_16x16x32_bf16 v[132:135], v[168:171], v[156:159], v[132:135]
	v_mfma_f32_16x16x32_bf16 v[156:159], v[172:175], v[156:159], v[100:103]
	v_mfma_f32_16x16x32_bf16 v[136:139], v[160:163], v[164:167], v[136:139]
	v_mfma_f32_16x16x32_bf16 v[160:163], v[176:179], v[164:167], v[112:115]
	v_mfma_f32_16x16x32_bf16 v[144:147], v[168:171], v[164:167], v[144:147]
	v_mfma_f32_16x16x32_bf16 v[84:87], v[172:175], v[164:167], v[108:111]
	ds_read_b128 v[104:107], v190 offset:192
	ds_read_b128 v[100:103], v190 offset:4544
	ds_read_b128 v[184:187], v190 offset:8896
	ds_read_b128 v[164:167], v190 offset:13248
	ds_read_b128 v[176:179], v191 offset:35008
	v_add_u32_e32 v108, v225, v227
	ds_read_b128 v[180:183], v108
	ds_read_b128 v[172:175], v191 offset:39360
	ds_read_b128 v[168:171], v245 offset:4352
	s_waitcnt lgkmcnt(3)
	v_mfma_f32_16x16x32_bf16 v[140:143], v[176:179], v[104:107], v[140:143]
; __device__ __forceinline__ unsigned cvt_pk_bf16(float lo, float hi) { unsigned r; asm volatile("v_cvt_pk_bf16_f32 %0, %1, %2" : "=v"(r) : "v"(lo), "v"(hi)); return r; }
; #define LAS __attribute__((address_space(3)))
; #define MFMA16(a, b, c) __builtin_amdgcn_mfma_f32_16x16x32_bf16((a), (b), (c), 0, 0, 0)
; #define CHAIN_BAR() do { asm volatile("s_waitcnt lgkmcnt(0)" ::: "memory"); __builtin_amdgcn_s_barrier(); asm volatile("" ::: "memory"); } while (0)
; template <bool STORE> __device__ __forceinline__ void ret_chain(LAS unsigned char* lds, int b, int h, bf16* Qb, const bf16* Kb, const bf16* Vb, const bf16* Gb, const f32x2* tab, float* s_out) {
;     ...
;             for (int ti = 0; ti < 4; ++ti)
; #pragma unroll
;                 for (int t = 0; t < 2; ++t) { if (32 * wc + 16 * t <= 64 * wr + 16 * ti + 15) acc_p[ti][t] = MFMA16(kf[t], qf[ti], acc_p[ti][t]);
;                     acc_o[ti][t] = MFMA16(sf[t], qf[ti], acc_o[ti][t]); }
;         }
;         CHAIN_BAR();
;         {
;             const float pscale = __expf(-lg * (float)Leff);
; #pragma unroll
;             for (int ti = 0; ti < 4; ++ti)
; #pragma unroll
;                 for (int t = 0; t < 2; ++t) {
;                     const int i = 64 * wr + 16 * ti + l15, jb = 32 * wc + 16 * t + 4 * quad;
;                     float p[4];
; #pragma unroll
;                     for (int r = 0; r < 4; ++r) p[r] = (jb + r <= i) ? acc_p[ti][t][r] * pscale : 0.f;
;                     u32x2 wv; wv.x = cvt_pk_bf16(p[0], p[1]); wv.y = cvt_pk_bf16(p[2], p[3]);
;                     *(LAS u32x2*)(lds + RG0 + i * PTB + jb * 2) = wv;
;                 }
;         }
;         CHAIN_BAR();
.LBB0_371:
	s_waitcnt lgkmcnt(2)
	v_mfma_f32_16x16x32_bf16 v[112:115], v[180:183], v[104:107], v[88:91]
	s_waitcnt lgkmcnt(1)
	v_mfma_f32_16x16x32_bf16 v[128:131], v[172:175], v[104:107], v[128:131]
.LBB0_373:
	s_waitcnt lgkmcnt(0)
	v_mfma_f32_16x16x32_bf16 v[108:111], v[168:171], v[104:107], v[148:151]
	v_mfma_f32_16x16x32_bf16 v[120:123], v[176:179], v[100:103], v[120:123]
	v_mfma_f32_16x16x32_bf16 v[104:107], v[180:183], v[100:103], v[96:99]
	v_mfma_f32_16x16x32_bf16 v[116:119], v[172:175], v[100:103], v[116:119]
	v_mfma_f32_16x16x32_bf16 v[100:103], v[168:171], v[100:103], v[92:95]
	v_mfma_f32_16x16x32_bf16 v[124:127], v[176:179], v[184:187], v[124:127]
	v_mfma_f32_16x16x32_bf16 v[96:99], v[180:183], v[184:187], v[152:155]
	v_mfma_f32_16x16x32_bf16 v[132:135], v[172:175], v[184:187], v[132:135]
	v_mfma_f32_16x16x32_bf16 v[92:95], v[168:171], v[184:187], v[156:159]
	v_mfma_f32_16x16x32_bf16 v[136:139], v[176:179], v[164:167], v[136:139]
	v_mfma_f32_16x16x32_bf16 v[88:91], v[180:183], v[164:167], v[160:163]
	v_mfma_f32_16x16x32_bf16 v[144:147], v[172:175], v[164:167], v[144:147]
	v_cvt_f32_ubyte0_e32 v148, s48
	v_mul_f32_e32 v172, s33, v148
	v_mul_f32_e32 v148, 0xbfb8aa3b, v172
	s_add_i32 s30, s46, s45
	v_exp_f32_e32 v148, v148
	s_addk_i32 s30, 0xff80
	s_and_b64 s[28:29], s[28:29], exec
	v_readlane_b32 s28, v255, 25
	v_mul_f32_e32 v141, v148, v141
	v_readlane_b32 s29, v255, 26
	v_mul_f32_e32 v142, v148, v142
	v_mul_f32_e32 v143, v148, v143
	v_cndmask_b32_e64 v141, 0, v141, s[28:29]
	v_readlane_b32 s28, v255, 27
	v_readlane_b32 s29, v255, 28
	v_mul_f32_e32 v128, v148, v128
	v_mul_f32_e32 v129, v148, v129
	v_cndmask_b32_e64 v142, v142, 0, s[28:29]
	v_readlane_b32 s28, v255, 29
	v_readlane_b32 s29, v255, 30
	v_mul_f32_e32 v130, v148, v130
	v_mul_f32_e32 v131, v148, v131
	v_cndmask_b32_e64 v143, v143, 0, s[28:29]
	v_readlane_b32 s28, v255, 31
	v_readlane_b32 s29, v255, 32
	v_mul_f32_e32 v120, v148, v120
	v_mul_f32_e32 v121, v148, v121
	v_cndmask_b32_e64 v128, v128, 0, s[28:29]
	v_readlane_b32 s28, v255, 33
	v_readlane_b32 s29, v255, 34
	v_mul_f32_e32 v122, v148, v122
	v_mul_f32_e32 v123, v148, v123
	v_cndmask_b32_e64 v129, v129, 0, s[28:29]
	v_readlane_b32 s28, v255, 35
	v_readlane_b32 s29, v255, 36
	v_mul_f32_e32 v140, v148, v140
	v_cndmask_b32_e64 v140, v140, 0, s[20:21]
	v_cndmask_b32_e64 v130, v130, 0, s[28:29]
	v_readlane_b32 s28, v255, 37
	v_readlane_b32 s29, v255, 38
	v_mul_f32_e32 v117, v148, v117
	s_waitcnt lgkmcnt(0)
	s_barrier
	v_cndmask_b32_e64 v131, v131, 0, s[28:29]
	v_readlane_b32 s28, v255, 39
	v_readlane_b32 s29, v255, 40
	v_cvt_pk_bf16_f32 v140, v140, v141
	v_cvt_pk_bf16_f32 v141, v142, v143
	v_add_u32_e32 v142, v228, v188
	ds_write_b64 v142, v[140:141]
	v_cndmask_b32_e64 v120, v120, 0, s[28:29]
	v_readlane_b32 s28, v255, 41
	v_readlane_b32 s29, v255, 42
	v_cvt_pk_bf16_f32 v128, v128, v129
	v_cvt_pk_bf16_f32 v129, v130, v131
	v_add_u32_e32 v130, v228, v229
	v_mul_f32_e32 v116, v148, v116
	v_cndmask_b32_e64 v121, 0, v121, s[28:29]
	v_readlane_b32 s28, v255, 43
	v_readlane_b32 s29, v255, 44
	v_mul_f32_e32 v118, v148, v118
	ds_write_b64 v130, v[128:129]
	v_cndmask_b32_e64 v122, v122, 0, s[28:29]
	v_readlane_b32 s28, v255, 45
	v_readlane_b32 s29, v255, 46
	v_cvt_pk_bf16_f32 v120, v120, v121
	v_cndmask_b32_e64 v116, v116, 0, s[20:21]
	v_mul_f32_e32 v119, v148, v119
	v_cndmask_b32_e64 v123, v123, 0, s[28:29]
	v_readlane_b32 s28, v255, 47
	v_readlane_b32 s29, v255, 48
	v_cvt_pk_bf16_f32 v121, v122, v123
	v_add_u32_e32 v122, v230, v188
	ds_write_b64 v122, v[120:121]
	v_cndmask_b32_e64 v117, v117, 0, s[28:29]
	v_readlane_b32 s28, v255, 49
	v_readlane_b32 s29, v255, 50
	v_cndmask_b32_e64 v119, v119, 0, s[50:51]
	v_cvt_pk_bf16_f32 v116, v116, v117
	v_cmp_gt_i32_e64 s[38:39], s48, v221
	v_cndmask_b32_e64 v118, v118, 0, s[28:29]
	v_cvt_pk_bf16_f32 v117, v118, v119
	v_add_u32_e32 v118, v230, v229
	ds_write_b64 v118, v[116:117]
	v_mul_f32_e32 v116, v148, v124
	v_mul_f32_e32 v117, v148, v125
	v_mul_f32_e32 v118, v148, v126
	v_cndmask_b32_e64 v116, v116, 0, s[52:53]
	v_cndmask_b32_e64 v117, 0, v117, s[54:55]
	v_cndmask_b32_e64 v118, v118, 0, s[56:57]
	v_mul_f32_e32 v119, v148, v127
	v_cndmask_b32_e64 v119, v119, 0, s[58:59]
	v_cvt_pk_bf16_f32 v116, v116, v117
	v_cvt_pk_bf16_f32 v117, v118, v119
	v_add_u32_e32 v118, v231, v188
	ds_write_b64 v118, v[116:117]
	v_mul_f32_e32 v116, v148, v132
	v_mul_f32_e32 v117, v148, v133
	v_mul_f32_e32 v118, v148, v134
	v_cndmask_b32_e64 v116, v116, 0, s[60:61]
	v_cndmask_b32_e64 v117, v117, 0, s[62:63]
	v_cndmask_b32_e64 v118, v118, 0, s[64:65]
	v_mul_f32_e32 v119, v148, v135
	v_cndmask_b32_e64 v119, v119, 0, s[66:67]
	v_cvt_pk_bf16_f32 v116, v116, v117
	v_cvt_pk_bf16_f32 v117, v118, v119
	v_add_u32_e32 v118, v231, v229
	ds_write_b64 v118, v[116:117]
	v_mul_f32_e32 v116, v148, v136
	v_mul_f32_e32 v117, v148, v137
	v_mul_f32_e32 v118, v148, v138
	v_cndmask_b32_e64 v116, v116, 0, s[68:69]
	v_cndmask_b32_e64 v117, 0, v117, s[70:71]
	v_cndmask_b32_e64 v118, v118, 0, s[72:73]
	v_mul_f32_e32 v119, v148, v139
	v_cndmask_b32_e64 v119, v119, 0, s[74:75]
	v_cvt_pk_bf16_f32 v116, v116, v117
	v_cvt_pk_bf16_f32 v117, v118, v119
	v_add_u32_e32 v118, v232, v188
	ds_write_b64 v118, v[116:117]
	v_mul_f32_e32 v116, v148, v144
	v_mul_f32_e32 v117, v148, v145
	v_mul_f32_e32 v118, v148, v146
	v_cndmask_b32_e64 v116, v116, 0, s[76:77]
	v_cndmask_b32_e64 v117, v117, 0, s[78:79]
	v_cndmask_b32_e64 v118, v118, 0, s[80:81]
	v_mul_f32_e32 v119, v148, v147
	v_cndmask_b32_e64 v119, v119, 0, s[82:83]
	v_cvt_pk_bf16_f32 v116, v116, v117
	v_cvt_pk_bf16_f32 v117, v118, v119
	v_add_u32_e32 v118, v232, v229
	s_cselect_b32 s47, s44, s30
	ds_write_b64 v118, v[116:117]
	v_cndmask_b32_e64 v116, 0, v221, s[38:39]
	v_add_u32_e32 v116, s47, v116
	v_ashrrev_i32_e32 v117, 31, v116
	v_lshlrev_b64 v[116:117], 11, v[116:117]
	s_waitcnt lgkmcnt(0)
	s_barrier
; #define MFMA16(a, b, c) __builtin_amdgcn_mfma_f32_16x16x32_bf16((a), (b), (c), 0, 0, 0)
; template <bool STORE> __device__ __forceinline__ void ret_chain(LAS unsigned char* lds, int b, int h, bf16* Qb, const bf16* Kb, const bf16* Vb, const bf16* Gb, const f32x2* tab, float* s_out) {
;     ...
;         u32x2 gpre[4][2];
; #pragma unroll
;         for (int ti = 0; ti < 4; ++ti) { const int i = 64 * wr + 16 * ti + l15; const size_t roff = (size_t)(row_base + (i < Leff ? i : 0)) * DM + h * HD;
; #pragma unroll
;             for (int t = 0; t < 2; ++t) gpre[ti][t] = *(const u32x2*)(Gb + roff + 32 * wc + 16 * t + 4 * quad); }
;     ...
;         {
;             const float sdec = __expf(lg * (float)Leff);
; #pragma unroll
;             for (int x = 0; x < 4; ++x)
; #pragma unroll
;                 for (int y = 0; y < 2; ++y) acc_s[x][y] = acc_s[x][y] * sdec;
;         }
; #pragma unroll
;         for (int ks = 0; ks < 4; ++ks) {
;             const int kel = ks * 32 + quad * 8;
;             bf16x8 pf[4], ktf[4], vf[2];
; #pragma unroll
;             for (int ti = 0; ti < 4; ++ti) { pf[ti] = ldfrag(lds + RG0, 64 * wr + 16 * ti + l15, kel); ktf[ti] = ldfrag_tr(lds + RG1, ks * 32, 64 * wr + 16 * ti, l15, quad); }
; #pragma unroll
;             for (int t = 0; t < 2; ++t) vf[t] = ldfrag_tr(lds + RG2, ks * 32, 32 * wc + 16 * t, l15, quad);
; #pragma unroll
;             for (int ti = 0; ti < 4; ++ti)
; #pragma unroll
;                 for (int t = 0; t < 2; ++t) { if (32 * ks <= 64 * wr + 16 * ti + 15) acc_o[ti][t] = MFMA16(vf[t], pf[ti], acc_o[ti][t]);
;                     acc_s[ti][t] = MFMA16(ktf[ti], vf[t], acc_s[ti][t]); }
	v_lshl_add_u64 v[116:117], v[194:195], 0, v[116:117]
	v_cmp_gt_i32_e64 s[34:35], s48, v201
	v_mfma_f32_16x16x32_bf16 v[84:87], v[168:171], v[164:167], v[84:87]
	global_load_dwordx2 v[170:171], v[116:117], off
	global_load_dwordx2 v[168:169], v[116:117], off offset:32
	v_cndmask_b32_e64 v116, 0, v201, s[34:35]
	v_add_u32_e32 v116, s47, v116
	v_ashrrev_i32_e32 v117, 31, v116
	v_lshlrev_b64 v[116:117], 11, v[116:117]
	v_lshl_add_u64 v[116:117], v[194:195], 0, v[116:117]
	v_cmp_gt_i32_e64 s[30:31], s48, v203
	global_load_dwordx2 v[166:167], v[116:117], off
	global_load_dwordx2 v[164:165], v[116:117], off offset:32
	v_cndmask_b32_e64 v116, 0, v203, s[30:31]
	v_add_u32_e32 v116, s47, v116
	v_ashrrev_i32_e32 v117, 31, v116
	v_lshlrev_b64 v[116:117], 11, v[116:117]
	v_lshl_add_u64 v[116:117], v[194:195], 0, v[116:117]
	v_cmp_gt_i32_e64 s[28:29], s48, v222
	global_load_dwordx2 v[162:163], v[116:117], off
	global_load_dwordx2 v[160:161], v[116:117], off offset:32
	v_cndmask_b32_e64 v116, 0, v222, s[28:29]
	v_add_u32_e32 v116, s47, v116
	v_ashrrev_i32_e32 v117, 31, v116
	v_lshlrev_b64 v[116:117], 11, v[116:117]
	v_lshl_add_u64 v[116:117], v[194:195], 0, v[116:117]
	global_load_dwordx2 v[158:159], v[116:117], off
	global_load_dwordx2 v[156:157], v[116:117], off offset:32
	ds_read_b128 v[152:155], v190
	ds_read_b64_tr_b16 v[148:149], v251 offset:34816
	ds_read_b64_tr_b16 v[150:151], v251 offset:35904
	ds_read_b128 v[144:147], v252
	ds_read_b64_tr_b16 v[140:141], v253 offset:34816
	ds_read_b64_tr_b16 v[142:143], v253 offset:35904
	ds_read_b128 v[136:139], v209
	ds_read_b64_tr_b16 v[132:133], v210 offset:34816
	ds_read_b64_tr_b16 v[134:135], v210 offset:35904
	ds_read_b128 v[124:127], v211
	ds_read_b64_tr_b16 v[116:117], v212 offset:34816
	ds_read_b64_tr_b16 v[118:119], v212 offset:35904
	ds_read_b64_tr_b16 v[130:131], v213 offset:1088
	ds_read_b64_tr_b16 v[128:129], v213
	ds_read_b64_tr_b16 v[120:121], v213 offset:32
	ds_read_b64_tr_b16 v[122:123], v213 offset:1120
	s_waitcnt lgkmcnt(2)
	v_mfma_f32_16x16x32_bf16 v[112:115], v[128:131], v[152:155], v[112:115]
.LBB0_387:
	v_mul_f32_e32 v172, 0x3fb8aa3b, v172
	v_exp_f32_e32 v172, v172
	s_nop 0
	v_pk_mul_f32 v[82:83], v[82:83], v[172:173] op_sel_hi:[1,0]
	v_pk_mul_f32 v[80:81], v[80:81], v[172:173] op_sel_hi:[1,0]
	s_waitcnt lgkmcnt(2)
	s_nop 0
	v_mfma_f32_16x16x32_bf16 v[80:83], v[148:151], v[128:131], v[80:83]
	s_waitcnt lgkmcnt(0)
	v_mfma_f32_16x16x32_bf16 v[108:111], v[120:123], v[152:155], v[108:111]
; #define MFMA16(a, b, c) __builtin_amdgcn_mfma_f32_16x16x32_bf16((a), (b), (c), 0, 0, 0)
; template <bool STORE> __device__ __forceinline__ void ret_chain(LAS unsigned char* lds, int b, int h, bf16* Qb, const bf16* Kb, const bf16* Vb, const bf16* Gb, const f32x2* tab, float* s_out) {
;     ...
;         for (int ks = 0; ks < 4; ++ks) {
;             const int kel = ks * 32 + quad * 8;
;             bf16x8 pf[4], ktf[4], vf[2];
; #pragma unroll
;             for (int ti = 0; ti < 4; ++ti) { pf[ti] = ldfrag(lds + RG0, 64 * wr + 16 * ti + l15, kel); ktf[ti] = ldfrag_tr(lds + RG1, ks * 32, 64 * wr + 16 * ti, l15, quad); }
; #pragma unroll
;             for (int t = 0; t < 2; ++t) vf[t] = ldfrag_tr(lds + RG2, ks * 32, 32 * wc + 16 * t, l15, quad);
; #pragma unroll
;             for (int ti = 0; ti < 4; ++ti)
; #pragma unroll
;                 for (int t = 0; t < 2; ++t) { if (32 * ks <= 64 * wr + 16 * ti + 15) acc_o[ti][t] = MFMA16(vf[t], pf[ti], acc_o[ti][t]);
;                     acc_s[ti][t] = MFMA16(ktf[ti], vf[t], acc_s[ti][t]); }
.LBB0_389:
	v_mov_b32_e32 v173, v172
	v_mov_b32_e32 v152, v172
	v_mov_b32_e32 v153, v172
	v_pk_mul_f32 v[78:79], v[78:79], v[152:153]
	v_pk_mul_f32 v[76:77], v[76:77], v[172:173]
	s_waitcnt lgkmcnt(0)
	s_nop 0
	v_mfma_f32_16x16x32_bf16 v[76:79], v[148:151], v[120:123], v[76:79]
	v_mfma_f32_16x16x32_bf16 v[104:107], v[128:131], v[144:147], v[104:107]
	v_pk_mul_f32 v[74:75], v[74:75], v[152:153]
	v_pk_mul_f32 v[72:73], v[72:73], v[172:173]
	s_nop 1
	v_mfma_f32_16x16x32_bf16 v[72:75], v[140:143], v[128:131], v[72:75]
	v_mfma_f32_16x16x32_bf16 v[100:103], v[120:123], v[144:147], v[100:103]
	v_mov_b32_e32 v144, v172
	v_mov_b32_e32 v145, v172
	v_pk_mul_f32 v[70:71], v[70:71], v[144:145]
	v_pk_mul_f32 v[68:69], v[68:69], v[172:173]
	s_nop 1
	v_mfma_f32_16x16x32_bf16 v[68:71], v[140:143], v[120:123], v[68:71]
	v_mfma_f32_16x16x32_bf16 v[96:99], v[128:131], v[136:139], v[96:99]
	v_pk_mul_f32 v[66:67], v[66:67], v[144:145]
	v_pk_mul_f32 v[64:65], v[64:65], v[172:173]
	s_nop 1
	v_mfma_f32_16x16x32_bf16 v[64:67], v[132:135], v[128:131], v[64:67]
	v_mfma_f32_16x16x32_bf16 v[92:95], v[120:123], v[136:139], v[92:95]
	v_mov_b32_e32 v136, v172
	v_mov_b32_e32 v137, v172
	v_pk_mul_f32 v[62:63], v[62:63], v[136:137]
	v_pk_mul_f32 v[60:61], v[60:61], v[172:173]
	s_nop 1
	v_mfma_f32_16x16x32_bf16 v[60:63], v[132:135], v[120:123], v[60:63]
	v_mfma_f32_16x16x32_bf16 v[88:91], v[128:131], v[124:127], v[88:91]
	v_pk_mul_f32 v[58:59], v[58:59], v[136:137]
	v_pk_mul_f32 v[56:57], v[56:57], v[172:173]
	s_nop 1
	v_mfma_f32_16x16x32_bf16 v[56:59], v[116:119], v[128:131], v[56:59]
	v_mfma_f32_16x16x32_bf16 v[84:87], v[120:123], v[124:127], v[84:87]
	v_mov_b32_e32 v124, v172
	v_mov_b32_e32 v125, v172
	v_pk_mul_f32 v[54:55], v[54:55], v[124:125]
	v_pk_mul_f32 v[52:53], v[52:53], v[172:173]
	s_nop 1
	v_mfma_f32_16x16x32_bf16 v[52:55], v[116:119], v[120:123], v[52:55]
	ds_read_b128 v[152:155], v190 offset:64
	ds_read_b64_tr_b16 v[148:149], v251 offset:43520
	ds_read_b64_tr_b16 v[150:151], v251 offset:44608
	ds_read_b128 v[144:147], v252 offset:64
	ds_read_b64_tr_b16 v[140:141], v253 offset:43520
	ds_read_b64_tr_b16 v[142:143], v253 offset:44608
	ds_read_b128 v[136:139], v209 offset:64
	ds_read_b64_tr_b16 v[132:133], v210 offset:43520
	ds_read_b64_tr_b16 v[134:135], v210 offset:44608
	ds_read_b128 v[120:123], v211 offset:64
	ds_read_b64_tr_b16 v[116:117], v212 offset:43520
	ds_read_b64_tr_b16 v[118:119], v212 offset:44608
	ds_read_b64_tr_b16 v[130:131], v213 offset:9792
	ds_read_b64_tr_b16 v[128:129], v213 offset:8704
	ds_read_b64_tr_b16 v[124:125], v213 offset:8736
	ds_read_b64_tr_b16 v[126:127], v213 offset:9824
	s_waitcnt lgkmcnt(2)
	v_mfma_f32_16x16x32_bf16 v[112:115], v[128:131], v[152:155], v[112:115]
.LBB0_403:
	s_waitcnt lgkmcnt(2)
	v_mfma_f32_16x16x32_bf16 v[80:83], v[148:151], v[128:131], v[80:83]
	s_waitcnt lgkmcnt(0)
	v_mfma_f32_16x16x32_bf16 v[108:111], v[124:127], v[152:155], v[108:111]
.LBB0_405:
	s_waitcnt lgkmcnt(0)
	v_mfma_f32_16x16x32_bf16 v[76:79], v[148:151], v[124:127], v[76:79]
	v_mfma_f32_16x16x32_bf16 v[104:107], v[128:131], v[144:147], v[104:107]
	v_mfma_f32_16x16x32_bf16 v[72:75], v[140:143], v[128:131], v[72:75]
	v_mfma_f32_16x16x32_bf16 v[100:103], v[124:127], v[144:147], v[100:103]
	v_mfma_f32_16x16x32_bf16 v[68:71], v[140:143], v[124:127], v[68:71]
	v_mfma_f32_16x16x32_bf16 v[96:99], v[128:131], v[136:139], v[96:99]
	v_mfma_f32_16x16x32_bf16 v[64:67], v[132:135], v[128:131], v[64:67]
	v_mfma_f32_16x16x32_bf16 v[92:95], v[124:127], v[136:139], v[92:95]
	v_mfma_f32_16x16x32_bf16 v[60:63], v[132:135], v[124:127], v[60:63]
	v_mfma_f32_16x16x32_bf16 v[88:91], v[128:131], v[120:123], v[88:91]
	v_mfma_f32_16x16x32_bf16 v[56:59], v[116:119], v[128:131], v[56:59]
	v_mfma_f32_16x16x32_bf16 v[84:87], v[124:127], v[120:123], v[84:87]
	v_mfma_f32_16x16x32_bf16 v[52:55], v[116:119], v[124:127], v[52:55]
	ds_read_b128 v[152:155], v190 offset:128
	ds_read_b64_tr_b16 v[148:149], v251 offset:52224
	ds_read_b64_tr_b16 v[150:151], v251 offset:53312
	ds_read_b128 v[144:147], v252 offset:128
	ds_read_b64_tr_b16 v[140:141], v253 offset:52224
	ds_read_b64_tr_b16 v[142:143], v253 offset:53312
	ds_read_b128 v[136:139], v209 offset:128
	ds_read_b64_tr_b16 v[132:133], v210 offset:52224
	ds_read_b64_tr_b16 v[134:135], v210 offset:53312
	ds_read_b128 v[120:123], v211 offset:128
	ds_read_b64_tr_b16 v[116:117], v212 offset:52224
	ds_read_b64_tr_b16 v[118:119], v212 offset:53312
	ds_read_b64_tr_b16 v[130:131], v213 offset:18496
	ds_read_b64_tr_b16 v[128:129], v213 offset:17408
	ds_read_b64_tr_b16 v[124:125], v213 offset:17440
	ds_read_b64_tr_b16 v[126:127], v213 offset:18528
	s_waitcnt lgkmcnt(2)
	v_mfma_f32_16x16x32_bf16 v[112:115], v[128:131], v[152:155], v[112:115]

; #define MFMA16(a, b, c) __builtin_amdgcn_mfma_f32_16x16x32_bf16((a), (b), (c), 0, 0, 0)
; template <bool STORE> __device__ __forceinline__ void ret_chain(LAS unsigned char* lds, int b, int h, bf16* Qb, const bf16* Kb, const bf16* Vb, const bf16* Gb, const f32x2* tab, float* s_out) {
;     ...
;         for (int ks = 0; ks < 4; ++ks) {
;             const int kel = ks * 32 + quad * 8;
;             bf16x8 pf[4], ktf[4], vf[2];
; #pragma unroll
;             for (int ti = 0; ti < 4; ++ti) { pf[ti] = ldfrag(lds + RG0, 64 * wr + 16 * ti + l15, kel); ktf[ti] = ldfrag_tr(lds + RG1, ks * 32, 64 * wr + 16 * ti, l15, quad); }
; #pragma unroll
;             for (int t = 0; t < 2; ++t) vf[t] = ldfrag_tr(lds + RG2, ks * 32, 32 * wc + 16 * t, l15, quad);
; #pragma unroll
;             for (int ti = 0; ti < 4; ++ti)
; #pragma unroll
;                 for (int t = 0; t < 2; ++t) { if (32 * ks <= 64 * wr + 16 * ti + 15) acc_o[ti][t] = MFMA16(vf[t], pf[ti], acc_o[ti][t]);
;                     acc_s[ti][t] = MFMA16(ktf[ti], vf[t], acc_s[ti][t]); }
.LBB0_421:
	s_waitcnt lgkmcnt(0)
	v_mfma_f32_16x16x32_bf16 v[76:79], v[148:151], v[124:127], v[76:79]
	v_mfma_f32_16x16x32_bf16 v[104:107], v[128:131], v[144:147], v[104:107]
	v_mfma_f32_16x16x32_bf16 v[72:75], v[140:143], v[128:131], v[72:75]
	v_mfma_f32_16x16x32_bf16 v[100:103], v[124:127], v[144:147], v[100:103]
	v_mfma_f32_16x16x32_bf16 v[68:71], v[140:143], v[124:127], v[68:71]
	v_mfma_f32_16x16x32_bf16 v[96:99], v[128:131], v[136:139], v[96:99]
	v_mfma_f32_16x16x32_bf16 v[64:67], v[132:135], v[128:131], v[64:67]
	v_mfma_f32_16x16x32_bf16 v[92:95], v[124:127], v[136:139], v[92:95]
	v_mfma_f32_16x16x32_bf16 v[60:63], v[132:135], v[124:127], v[60:63]
	v_mfma_f32_16x16x32_bf16 v[88:91], v[128:131], v[120:123], v[88:91]
	v_mfma_f32_16x16x32_bf16 v[56:59], v[116:119], v[128:131], v[56:59]
	v_mfma_f32_16x16x32_bf16 v[84:87], v[124:127], v[120:123], v[84:87]
	v_mfma_f32_16x16x32_bf16 v[52:55], v[116:119], v[124:127], v[52:55]
	ds_read_b128 v[152:155], v190 offset:192
	ds_read_b64_tr_b16 v[148:149], v251 offset:60928
	ds_read_b64_tr_b16 v[150:151], v251 offset:62016
	ds_read_b128 v[144:147], v252 offset:192
	ds_read_b64_tr_b16 v[140:141], v253 offset:60928
	ds_read_b64_tr_b16 v[142:143], v253 offset:62016
	ds_read_b128 v[136:139], v209 offset:192
	ds_read_b64_tr_b16 v[132:133], v210 offset:60928
	ds_read_b64_tr_b16 v[134:135], v210 offset:62016
	ds_read_b128 v[120:123], v211 offset:192
	ds_read_b64_tr_b16 v[116:117], v212 offset:60928
	ds_read_b64_tr_b16 v[118:119], v212 offset:62016
	ds_read_b64_tr_b16 v[130:131], v213 offset:27200
	ds_read_b64_tr_b16 v[128:129], v213 offset:26112
	ds_read_b64_tr_b16 v[124:125], v213 offset:26144
	ds_read_b64_tr_b16 v[126:127], v213 offset:27232
	s_waitcnt lgkmcnt(2)
	v_mfma_f32_16x16x32_bf16 v[112:115], v[128:131], v[152:155], v[112:115]

; #define LAS __attribute__((address_space(3)))
; #define MFMA16(a, b, c) __builtin_amdgcn_mfma_f32_16x16x32_bf16((a), (b), (c), 0, 0, 0)
; template <bool STORE> __device__ __forceinline__ void ret_chain(LAS unsigned char* lds, int b, int h, bf16* Qb, const bf16* Kb, const bf16* Vb, const bf16* Gb, const f32x2* tab, float* s_out) {
;     ...
;         for (int ks = 0; ks < 4; ++ks) {
;             const int kel = ks * 32 + quad * 8;
;             bf16x8 pf[4], ktf[4], vf[2];
; #pragma unroll
;             for (int ti = 0; ti < 4; ++ti) { pf[ti] = ldfrag(lds + RG0, 64 * wr + 16 * ti + l15, kel); ktf[ti] = ldfrag_tr(lds + RG1, ks * 32, 64 * wr + 16 * ti, l15, quad); }
; #pragma unroll
;             for (int t = 0; t < 2; ++t) vf[t] = ldfrag_tr(lds + RG2, ks * 32, 32 * wc + 16 * t, l15, quad);
; #pragma unroll
;             for (int ti = 0; ti < 4; ++ti)
; #pragma unroll
;                 for (int t = 0; t < 2; ++t) { if (32 * ks <= 64 * wr + 16 * ti + 15) acc_o[ti][t] = MFMA16(vf[t], pf[ti], acc_o[ti][t]);
;                     acc_s[ti][t] = MFMA16(ktf[ti], vf[t], acc_s[ti][t]); }
;         }
;         LAS f32x2* stats = (LAS f32x2*)(lds + RG4);
; #pragma unroll
;         for (int ti = 0; ti < 4; ++ti) {
;             float s = 0.f, q = 0.f;
; #pragma unroll
;             for (int t = 0; t < 2; ++t)
; #pragma unroll
;                 for (int r = 0; r < 4; ++r) { const float x = acc_o[ti][t][r]; s += x; q += x * x; }
;             s += __shfl_xor(s, 16); s += __shfl_xor(s, 32); q += __shfl_xor(q, 16); q += __shfl_xor(q, 32);
;             if (quad == 0) stats[(64 * wr + 16 * ti + l15) * 4 + wc] = (f32x2){s, q};
.LBB0_437:
	s_waitcnt lgkmcnt(0)
	v_mfma_f32_16x16x32_bf16 v[76:79], v[148:151], v[124:127], v[76:79]
	v_mfma_f32_16x16x32_bf16 v[104:107], v[128:131], v[144:147], v[104:107]
	s_or_b64 exec, exec, vcc
	v_mfma_f32_16x16x32_bf16 v[72:75], v[140:143], v[128:131], v[72:75]
	s_and_saveexec_b64 vcc, s[0:1]
	v_mfma_f32_16x16x32_bf16 v[100:103], v[124:127], v[144:147], v[100:103]
	s_or_b64 exec, exec, vcc
	v_mfma_f32_16x16x32_bf16 v[68:71], v[140:143], v[124:127], v[68:71]
	s_and_saveexec_b64 vcc, s[22:23]
	v_mfma_f32_16x16x32_bf16 v[96:99], v[128:131], v[136:139], v[96:99]
	s_or_b64 exec, exec, vcc
	v_mfma_f32_16x16x32_bf16 v[64:67], v[132:135], v[128:131], v[64:67]
	s_and_saveexec_b64 vcc, s[22:23]
	v_mfma_f32_16x16x32_bf16 v[92:95], v[124:127], v[136:139], v[92:95]
	s_or_b64 exec, exec, vcc
	v_mfma_f32_16x16x32_bf16 v[60:63], v[132:135], v[124:127], v[60:63]
	s_and_saveexec_b64 vcc, s[24:25]
	v_mfma_f32_16x16x32_bf16 v[88:91], v[128:131], v[120:123], v[88:91]
	s_or_b64 exec, exec, vcc
	v_mfma_f32_16x16x32_bf16 v[56:59], v[116:119], v[128:131], v[56:59]
	s_and_saveexec_b64 vcc, s[24:25]
	v_mfma_f32_16x16x32_bf16 v[84:87], v[124:127], v[120:123], v[84:87]
	s_or_b64 exec, exec, vcc
	v_mfma_f32_16x16x32_bf16 v[52:55], v[116:119], v[124:127], v[52:55]
	v_and_b32_e32 v117, 64, v208
	v_xor_b32_e32 v116, 16, v208
	v_add_u32_e32 v117, 64, v117
	v_cmp_lt_i32_e32 vcc, v116, v117
	v_pk_mul_f32 v[118:119], v[112:113], v[112:113]
	s_nop 0
	v_cndmask_b32_e32 v116, v208, v116, vcc
	v_lshlrev_b32_e32 v121, 2, v116
	v_xor_b32_e32 v116, 32, v208
	v_cmp_lt_i32_e32 vcc, v116, v117
	v_fmac_f32_e32 v119, v112, v112
	s_nop 0
	v_cndmask_b32_e32 v116, v208, v116, vcc
	v_lshlrev_b32_e32 v120, 2, v116
	v_add_f32_e32 v116, 0, v112
	v_add_f32_e32 v116, v113, v116
	v_add_f32_e32 v122, v114, v116
	v_pk_mul_f32 v[116:117], v[114:115], v[114:115]
	s_nop 0
	v_add_f32_e32 v118, v116, v119
	v_add_f32_e32 v116, v115, v122
	v_add_f32_e32 v119, v116, v108
	v_pk_mov_b32 v[116:117], v[114:115], v[108:109] op_sel:[1,0]
	v_pk_mul_f32 v[122:123], v[108:109], v[108:109]
	v_pk_mul_f32 v[116:117], v[116:117], v[116:117]
	s_nop 0
	v_add_f32_e32 v116, v116, v118
	v_add_f32_e32 v117, v116, v117
	v_add_f32_e32 v116, v109, v119
	v_pk_mul_f32 v[118:119], v[110:111], v[110:111]
	v_add_f32_e32 v117, v123, v117
	v_add_f32_e32 v116, v110, v116
	v_add_f32_e32 v119, v118, v117
	v_mul_f32_e32 v117, v111, v111
	v_mov_b32_e32 v118, v111
	v_pk_add_f32 v[116:117], v[118:119], v[116:117]
	ds_bpermute_b32 v118, v121, v116
	ds_bpermute_b32 v119, v121, v117
	s_waitcnt lgkmcnt(0)
	v_pk_add_f32 v[116:117], v[116:117], v[118:119]
	ds_bpermute_b32 v118, v120, v116
	ds_bpermute_b32 v119, v120, v117
	s_and_saveexec_b64 vcc, s[26:27]
	s_cbranch_execz .LBB0_451
	s_waitcnt lgkmcnt(0)
	v_pk_add_f32 v[116:117], v[116:117], v[118:119]
	ds_write_b64 v206, v[116:117]
